# previous stack + TOPK barriers skipped for wave-local bitonic steps + conv_weights row offsets by one multiply and seven adds
# speedup vs baseline: 1.0263x; 1.0030x over previous
.LBB0_58:
	v_mul_lo_u32 v34, s37, v64
	v_mul_lo_u32 v35, s36, v81
	v_mad_u64_u32 v[32:33], s[38:39], s36, v64, 0
	s_lshl_b64 s[98:99], s[36:37], 3
	v_add3_u32 v33, v33, v35, v34
	v_lshl_add_u64 v[34:35], v[32:33], 0, s[98:99]
	v_lshl_add_u64 v[40:41], v[34:35], 0, s[98:99]
	v_lshl_add_u64 v[42:43], v[40:41], 0, s[98:99]
	v_lshl_add_u64 v[48:49], v[42:43], 0, s[98:99]
	v_lshl_add_u64 v[50:51], v[48:49], 0, s[98:99]
	v_lshl_add_u64 v[56:57], v[50:51], 0, s[98:99]
	v_lshl_add_u64 v[58:59], v[56:57], 0, s[98:99]
	v_lshl_add_u64 v[32:33], v[32:33], 2, s[6:7]
	v_lshl_add_u64 v[34:35], v[34:35], 2, s[6:7]
	v_lshl_add_u64 v[40:41], v[40:41], 2, s[6:7]
	v_lshl_add_u64 v[42:43], v[42:43], 2, s[6:7]
	v_lshl_add_u64 v[48:49], v[48:49], 2, s[6:7]
	v_lshl_add_u64 v[50:51], v[50:51], 2, s[6:7]
	v_lshl_add_u64 v[56:57], v[56:57], 2, s[6:7]
	v_lshl_add_u64 v[58:59], v[58:59], 2, s[6:7]
	v_lshl_add_u64 v[32:33], v[32:33], 0, v[68:69]
	v_lshl_add_u64 v[36:37], v[34:35], 0, v[68:69]
	v_lshl_add_u64 v[40:41], v[40:41], 0, v[68:69]
	v_lshl_add_u64 v[44:45], v[42:43], 0, v[68:69]
	v_lshl_add_u64 v[48:49], v[48:49], 0, v[68:69]
	v_lshl_add_u64 v[52:53], v[50:51], 0, v[68:69]
	v_lshl_add_u64 v[56:57], v[56:57], 0, v[68:69]
	v_lshl_add_u64 v[60:61], v[58:59], 0, v[68:69]
	global_load_dwordx4 v[32:35], v[32:33], off nt
	s_nop 0
	global_load_dwordx4 v[36:39], v[36:37], off nt
	s_nop 0
	global_load_dwordx4 v[40:43], v[40:41], off nt
	s_nop 0
	global_load_dwordx4 v[44:47], v[44:45], off nt
	s_nop 0
	global_load_dwordx4 v[48:51], v[48:49], off nt
	s_nop 0
	global_load_dwordx4 v[52:55], v[52:53], off nt
	s_nop 0
	global_load_dwordx4 v[56:59], v[56:57], off nt
	s_nop 0
	global_load_dwordx4 v[60:63], v[60:61], off nt

.LBB0_595:
	v_mul_lo_u32 v36, s7, v66
	v_mul_lo_u32 v37, s6, v81
	v_mad_u64_u32 v[34:35], s[30:31], s6, v66, 0
	s_lshl_b64 s[98:99], s[6:7], 3
	v_add3_u32 v35, v35, v37, v36
	v_lshl_add_u64 v[36:37], v[34:35], 0, s[98:99]
	v_lshl_add_u64 v[42:43], v[36:37], 0, s[98:99]
	v_lshl_add_u64 v[44:45], v[42:43], 0, s[98:99]
	v_lshl_add_u64 v[50:51], v[44:45], 0, s[98:99]
	v_lshl_add_u64 v[52:53], v[50:51], 0, s[98:99]
	v_lshl_add_u64 v[58:59], v[52:53], 0, s[98:99]
	v_lshl_add_u64 v[60:61], v[58:59], 0, s[98:99]
	v_lshl_add_u64 v[34:35], v[34:35], 2, s[4:5]
	v_lshl_add_u64 v[36:37], v[36:37], 2, s[4:5]
	v_lshl_add_u64 v[42:43], v[42:43], 2, s[4:5]
	v_lshl_add_u64 v[44:45], v[44:45], 2, s[4:5]
	v_lshl_add_u64 v[50:51], v[50:51], 2, s[4:5]
	v_lshl_add_u64 v[52:53], v[52:53], 2, s[4:5]
	v_lshl_add_u64 v[58:59], v[58:59], 2, s[4:5]
	v_lshl_add_u64 v[60:61], v[60:61], 2, s[4:5]
	v_lshl_add_u64 v[34:35], v[34:35], 0, v[0:1]
	v_lshl_add_u64 v[38:39], v[36:37], 0, v[0:1]
	v_lshl_add_u64 v[42:43], v[42:43], 0, v[0:1]
	v_lshl_add_u64 v[46:47], v[44:45], 0, v[0:1]
	v_lshl_add_u64 v[50:51], v[50:51], 0, v[0:1]
	v_lshl_add_u64 v[54:55], v[52:53], 0, v[0:1]
	v_lshl_add_u64 v[58:59], v[58:59], 0, v[0:1]
	v_lshl_add_u64 v[62:63], v[60:61], 0, v[0:1]
	global_load_dwordx4 v[34:37], v[34:35], off nt
	s_nop 0
	global_load_dwordx4 v[38:41], v[38:39], off nt
	s_nop 0
	global_load_dwordx4 v[42:45], v[42:43], off nt
	s_nop 0
	global_load_dwordx4 v[46:49], v[46:47], off nt
	s_nop 0
	global_load_dwordx4 v[50:53], v[50:51], off nt
	s_nop 0
	global_load_dwordx4 v[54:57], v[54:55], off nt
	s_nop 0
	global_load_dwordx4 v[58:61], v[58:59], off nt
	s_nop 0
	global_load_dwordx4 v[62:65], v[62:63], off nt

.LBB0_702:
	v_mul_lo_u32 v36, s7, v66
	v_mul_lo_u32 v37, s6, v81
	v_mad_u64_u32 v[34:35], s[34:35], s6, v66, 0
	s_lshl_b64 s[98:99], s[6:7], 3
	v_add3_u32 v35, v35, v37, v36
	v_lshl_add_u64 v[36:37], v[34:35], 0, s[98:99]
	v_lshl_add_u64 v[42:43], v[36:37], 0, s[98:99]
	v_lshl_add_u64 v[44:45], v[42:43], 0, s[98:99]
	v_lshl_add_u64 v[50:51], v[44:45], 0, s[98:99]
	v_lshl_add_u64 v[52:53], v[50:51], 0, s[98:99]
	v_lshl_add_u64 v[58:59], v[52:53], 0, s[98:99]
	v_lshl_add_u64 v[60:61], v[58:59], 0, s[98:99]
	v_lshl_add_u64 v[34:35], v[34:35], 2, s[4:5]
	v_lshl_add_u64 v[36:37], v[36:37], 2, s[4:5]
	v_lshl_add_u64 v[42:43], v[42:43], 2, s[4:5]
	v_lshl_add_u64 v[44:45], v[44:45], 2, s[4:5]
	v_lshl_add_u64 v[50:51], v[50:51], 2, s[4:5]
	v_lshl_add_u64 v[52:53], v[52:53], 2, s[4:5]
	v_lshl_add_u64 v[58:59], v[58:59], 2, s[4:5]
	v_lshl_add_u64 v[60:61], v[60:61], 2, s[4:5]
	v_lshl_add_u64 v[34:35], v[34:35], 0, v[0:1]
	v_lshl_add_u64 v[38:39], v[36:37], 0, v[0:1]
	v_lshl_add_u64 v[42:43], v[42:43], 0, v[0:1]
	v_lshl_add_u64 v[46:47], v[44:45], 0, v[0:1]
	v_lshl_add_u64 v[50:51], v[50:51], 0, v[0:1]
	v_lshl_add_u64 v[54:55], v[52:53], 0, v[0:1]
	v_lshl_add_u64 v[58:59], v[58:59], 0, v[0:1]
	v_lshl_add_u64 v[62:63], v[60:61], 0, v[0:1]
	global_load_dwordx4 v[34:37], v[34:35], off nt
	s_nop 0
	global_load_dwordx4 v[38:41], v[38:39], off nt
	s_nop 0
	global_load_dwordx4 v[42:45], v[42:43], off nt
	s_nop 0
	global_load_dwordx4 v[46:49], v[46:47], off nt
	s_nop 0
	global_load_dwordx4 v[50:53], v[50:51], off nt
	s_nop 0
	global_load_dwordx4 v[54:57], v[54:55], off nt
	s_nop 0
	global_load_dwordx4 v[58:61], v[58:59], off nt
	s_nop 0
	global_load_dwordx4 v[62:65], v[62:63], off nt

.LBB0_972:
	v_mul_lo_u32 v36, s7, v66
	v_mul_lo_u32 v37, s6, v81
	v_mad_u64_u32 v[34:35], s[26:27], s6, v66, 0
	s_lshl_b64 s[98:99], s[6:7], 3
	v_add3_u32 v35, v35, v37, v36
	v_lshl_add_u64 v[36:37], v[34:35], 0, s[98:99]
	v_lshl_add_u64 v[42:43], v[36:37], 0, s[98:99]
	v_lshl_add_u64 v[44:45], v[42:43], 0, s[98:99]
	v_lshl_add_u64 v[50:51], v[44:45], 0, s[98:99]
	v_lshl_add_u64 v[52:53], v[50:51], 0, s[98:99]
	v_lshl_add_u64 v[58:59], v[52:53], 0, s[98:99]
	v_lshl_add_u64 v[60:61], v[58:59], 0, s[98:99]
	v_lshl_add_u64 v[34:35], v[34:35], 2, s[4:5]
	v_lshl_add_u64 v[36:37], v[36:37], 2, s[4:5]
	v_lshl_add_u64 v[42:43], v[42:43], 2, s[4:5]
	v_lshl_add_u64 v[44:45], v[44:45], 2, s[4:5]
	v_lshl_add_u64 v[50:51], v[50:51], 2, s[4:5]
	v_lshl_add_u64 v[52:53], v[52:53], 2, s[4:5]
	v_lshl_add_u64 v[58:59], v[58:59], 2, s[4:5]
	v_lshl_add_u64 v[60:61], v[60:61], 2, s[4:5]
	v_lshl_add_u64 v[34:35], v[34:35], 0, v[0:1]
	v_lshl_add_u64 v[38:39], v[36:37], 0, v[0:1]
	v_lshl_add_u64 v[42:43], v[42:43], 0, v[0:1]
	v_lshl_add_u64 v[46:47], v[44:45], 0, v[0:1]
	v_lshl_add_u64 v[50:51], v[50:51], 0, v[0:1]
	v_lshl_add_u64 v[54:55], v[52:53], 0, v[0:1]
	v_lshl_add_u64 v[58:59], v[58:59], 0, v[0:1]
	v_lshl_add_u64 v[62:63], v[60:61], 0, v[0:1]
	global_load_dwordx4 v[34:37], v[34:35], off nt
	s_nop 0
	global_load_dwordx4 v[38:41], v[38:39], off nt
	s_nop 0
	global_load_dwordx4 v[42:45], v[42:43], off nt
	s_nop 0
	global_load_dwordx4 v[46:49], v[46:47], off nt
	s_nop 0
	global_load_dwordx4 v[50:53], v[50:51], off nt
	s_nop 0
	global_load_dwordx4 v[54:57], v[54:55], off nt
	s_nop 0
	global_load_dwordx4 v[58:61], v[58:59], off nt
	s_nop 0
	global_load_dwordx4 v[62:65], v[62:63], off nt

.LBB0_1349:
	s_or_b64 exec, exec, s[12:13]
	s_lshr_b32 s6, s33, 1
	s_cmp_lt_u32 s33, 2
	s_mov_b32 s33, s6
	s_waitcnt lgkmcnt(0)
	s_cselect_b32 s98, 1, 0
	s_cmp_ge_u32 s6, 64
	s_cbranch_scc1 .Ltk_bar
	s_cmp_eq_u32 s98, 0
	s_cbranch_scc1 .Ltk_nobar
	s_cmp_lt_u32 s31, 0x80
	s_cbranch_scc1 .Ltk_nobar

.Ltk_nobar:
	s_cmp_lg_u32 s98, 0
	s_cbranch_scc1 .LBB0_1347
